# grid barrier: non-leader CUs poll the top-level generation word directly (one serialized hop less per barrier)
# baseline (speedup 1.0000x reference)
; __device__ __forceinline__ unsigned xb_ld(unsigned* p)              { return __hip_atomic_load(p, __ATOMIC_RELAXED, __HIP_MEMORY_SCOPE_AGENT); }
; __device__ __forceinline__ unsigned xb_add(unsigned* p, unsigned v) { return __hip_atomic_fetch_add(p, v, __ATOMIC_RELAXED, __HIP_MEMORY_SCOPE_AGENT); }
; #define XB_SPIN(cond, bar) do { unsigned _sp = 0; while (cond) { __builtin_amdgcn_s_sleep(1); \
;     if ((++_sp & 255u) == 0u) { if (xb_ld(&(bar)[XB_TMO])) break; if (_sp > XB_SPIN_CAP) { atomicAdd(&(bar)[XB_TMO], 1u); break; } } } } while (0)
; __device__ __forceinline__ void xcd_barrier(const XcdBarrier& b) {
;     ...
;         const unsigned old = xb_add(&bar[XB_XSUB(b.x)], 1u);
;         const unsigned gen = old / nloc;
;         if (old + 1u == (gen + 1u) * nloc) {
;             __builtin_amdgcn_fence(__ATOMIC_RELEASE, "agent");
;             asm volatile("s_waitcnt vmcnt(0)" ::: "memory");
;             const unsigned og = xb_add(&bar[XB_TOP], 1u);
;             const unsigned tg = og / nx;
;             if (og + 1u == (tg + 1u) * nx) xb_add(&bar[XB_TOPGEN], 1u);
;             else XB_SPIN(xb_ld(&bar[XB_TOPGEN]) == tg, bar);
;             __builtin_amdgcn_fence(__ATOMIC_ACQUIRE, "agent");
;             xb_add(&bar[XB_XGEN(b.x)], 1u);
;             asm volatile("s_waitcnt vmcnt(0)" ::: "memory");
;         } else {
;             XB_SPIN(xb_ld(&bar[XB_XGEN(b.x)]) == gen, bar);
;             __builtin_amdgcn_fence(__ATOMIC_ACQUIRE, "agent");
;             asm volatile("s_waitcnt vmcnt(0)" ::: "memory");
;         }
.LBB0_93:
	s_or_b64 exec, exec, s[18:19]
	v_cvt_f32_u32_e32 v4, v2
	s_waitcnt vmcnt(0)
	v_readfirstlane_b32 s2, v3
	v_sub_u32_e32 v3, 0, v2
	v_rcp_iflag_f32_e32 v4, v4
	v_add_u32_e32 v5, s2, v1
	v_mul_f32_e32 v4, 0x4f7ffffe, v4
	v_cvt_u32_f32_e32 v4, v4
	v_mul_lo_u32 v1, v3, v4
	v_mul_hi_u32 v1, v4, v1
	v_add_u32_e32 v1, v4, v1
	v_mul_hi_u32 v1, v5, v1
	v_mul_lo_u32 v3, v1, v2
	v_sub_u32_e32 v3, v5, v3
	v_add_u32_e32 v4, 1, v1
	v_cmp_ge_u32_e32 vcc, v3, v2
	s_nop 1
	v_cndmask_b32_e32 v1, v1, v4, vcc
	v_sub_u32_e32 v4, v3, v2
	v_cndmask_b32_e32 v3, v3, v4, vcc
	v_add_u32_e32 v4, 1, v1
	v_cmp_ge_u32_e32 vcc, v3, v2
	v_add_u32_e32 v3, 1, v5
	s_nop 0
	v_cndmask_b32_e32 v1, v1, v4, vcc
	v_mul_lo_u32 v4, v2, v1
	v_add_u32_e32 v2, v4, v2
	v_cmp_ne_u32_e32 vcc, v3, v2
	s_and_saveexec_b64 s[2:3], vcc
	s_xor_b64 s[14:15], exec, s[2:3]
	s_cbranch_execz .LBB0_107
	s_waitcnt lgkmcnt(0)
	s_add_u32 s22, s6, 0x7500
	s_addc_u32 s23, s7, 0
	v_mov_b32_e32 v0, 0
	global_load_dword v0, v0, s[22:23] sc1
	s_waitcnt vmcnt(0)
	v_cmp_eq_u32_e32 vcc, v0, v1
	s_and_saveexec_b64 s[18:19], vcc
	s_cbranch_execz .LBB0_106
	s_add_u32 s20, s6, 0x4200
	s_addc_u32 s21, s7, 0
	s_mov_b32 s2, 1
	s_mov_b64 s[24:25], 0
	v_mov_b32_e32 v0, 0
	s_branch .LBB0_97

; __device__ __forceinline__ unsigned xb_ld(unsigned* p)              { return __hip_atomic_load(p, __ATOMIC_RELAXED, __HIP_MEMORY_SCOPE_AGENT); }
; __device__ __forceinline__ unsigned xb_add(unsigned* p, unsigned v) { return __hip_atomic_fetch_add(p, v, __ATOMIC_RELAXED, __HIP_MEMORY_SCOPE_AGENT); }
; #define XB_SPIN(cond, bar) do { unsigned _sp = 0; while (cond) { __builtin_amdgcn_s_sleep(1); \
;     if ((++_sp & 255u) == 0u) { if (xb_ld(&(bar)[XB_TMO])) break; if (_sp > XB_SPIN_CAP) { atomicAdd(&(bar)[XB_TMO], 1u); break; } } } } while (0)
; __device__ __forceinline__ void xcd_barrier(const XcdBarrier& b) {
;     ...
;         const unsigned old = xb_add(&bar[XB_XSUB(b.x)], 1u);
;         const unsigned gen = old / nloc;
;         if (old + 1u == (gen + 1u) * nloc) {
;             __builtin_amdgcn_fence(__ATOMIC_RELEASE, "agent");
;             asm volatile("s_waitcnt vmcnt(0)" ::: "memory");
;             const unsigned og = xb_add(&bar[XB_TOP], 1u);
;             const unsigned tg = og / nx;
;             if (og + 1u == (tg + 1u) * nx) xb_add(&bar[XB_TOPGEN], 1u);
;             else XB_SPIN(xb_ld(&bar[XB_TOPGEN]) == tg, bar);
;             __builtin_amdgcn_fence(__ATOMIC_ACQUIRE, "agent");
;             xb_add(&bar[XB_XGEN(b.x)], 1u);
;             asm volatile("s_waitcnt vmcnt(0)" ::: "memory");
;         } else {
;             XB_SPIN(xb_ld(&bar[XB_XGEN(b.x)]) == gen, bar);
;             __builtin_amdgcn_fence(__ATOMIC_ACQUIRE, "agent");
;             asm volatile("s_waitcnt vmcnt(0)" ::: "memory");
;         }
.LBB0_368:
	s_or_b64 exec, exec, s[14:15]
	v_cvt_f32_u32_e32 v5, v3
	s_waitcnt vmcnt(0)
	v_readfirstlane_b32 s2, v4
	v_sub_u32_e32 v4, 0, v3
	v_rcp_iflag_f32_e32 v5, v5
	v_add_u32_e32 v6, s2, v2
	v_mul_f32_e32 v5, 0x4f7ffffe, v5
	v_cvt_u32_f32_e32 v5, v5
	v_mul_lo_u32 v2, v4, v5
	v_mul_hi_u32 v2, v5, v2
	v_add_u32_e32 v2, v5, v2
	v_mul_hi_u32 v2, v6, v2
	v_mul_lo_u32 v4, v2, v3
	v_sub_u32_e32 v4, v6, v4
	v_add_u32_e32 v5, 1, v2
	v_cmp_ge_u32_e32 vcc, v4, v3
	s_nop 1
	v_cndmask_b32_e32 v2, v2, v5, vcc
	v_sub_u32_e32 v5, v4, v3
	v_cndmask_b32_e32 v4, v4, v5, vcc
	v_add_u32_e32 v5, 1, v2
	v_cmp_ge_u32_e32 vcc, v4, v3
	v_add_u32_e32 v4, 1, v6
	s_nop 0
	v_cndmask_b32_e32 v2, v2, v5, vcc
	v_mul_lo_u32 v5, v3, v2
	v_add_u32_e32 v3, v5, v3
	v_cmp_ne_u32_e32 vcc, v4, v3
	s_and_saveexec_b64 s[12:13], vcc
	s_xor_b64 s[12:13], exec, s[12:13]
	s_cbranch_execz .LBB0_382
	s_waitcnt lgkmcnt(0)
	s_add_u32 s40, s6, 0x7500
	s_addc_u32 s41, s7, 0
	v_mov_b32_e32 v0, 0
	global_load_dword v0, v0, s[40:41] sc1
	s_waitcnt vmcnt(0)
	v_cmp_eq_u32_e32 vcc, v0, v2
	s_and_saveexec_b64 s[14:15], vcc
	s_cbranch_execz .LBB0_381
	s_add_u32 s38, s6, 0x4200
	s_addc_u32 s39, s7, 0
	s_mov_b32 s2, 1
	s_mov_b64 s[42:43], 0
	s_branch .LBB0_372

; __device__ __forceinline__ unsigned xb_ld(unsigned* p)              { return __hip_atomic_load(p, __ATOMIC_RELAXED, __HIP_MEMORY_SCOPE_AGENT); }
; __device__ __forceinline__ unsigned xb_add(unsigned* p, unsigned v) { return __hip_atomic_fetch_add(p, v, __ATOMIC_RELAXED, __HIP_MEMORY_SCOPE_AGENT); }
; #define XB_SPIN(cond, bar) do { unsigned _sp = 0; while (cond) { __builtin_amdgcn_s_sleep(1); \
;     if ((++_sp & 255u) == 0u) { if (xb_ld(&(bar)[XB_TMO])) break; if (_sp > XB_SPIN_CAP) { atomicAdd(&(bar)[XB_TMO], 1u); break; } } } } while (0)
; __device__ __forceinline__ void xcd_barrier(const XcdBarrier& b) {
;     ...
;         const unsigned old = xb_add(&bar[XB_XSUB(b.x)], 1u);
;         const unsigned gen = old / nloc;
;         if (old + 1u == (gen + 1u) * nloc) {
;             __builtin_amdgcn_fence(__ATOMIC_RELEASE, "agent");
;             asm volatile("s_waitcnt vmcnt(0)" ::: "memory");
;             const unsigned og = xb_add(&bar[XB_TOP], 1u);
;             const unsigned tg = og / nx;
;             if (og + 1u == (tg + 1u) * nx) xb_add(&bar[XB_TOPGEN], 1u);
;             else XB_SPIN(xb_ld(&bar[XB_TOPGEN]) == tg, bar);
;             __builtin_amdgcn_fence(__ATOMIC_ACQUIRE, "agent");
;             xb_add(&bar[XB_XGEN(b.x)], 1u);
;             asm volatile("s_waitcnt vmcnt(0)" ::: "memory");
;         } else {
;             XB_SPIN(xb_ld(&bar[XB_XGEN(b.x)]) == gen, bar);
;             __builtin_amdgcn_fence(__ATOMIC_ACQUIRE, "agent");
;             asm volatile("s_waitcnt vmcnt(0)" ::: "memory");
;         }
.LBB0_499:
	s_or_b64 exec, exec, s[40:41]
	v_cvt_f32_u32_e32 v5, v3
	s_waitcnt vmcnt(0)
	v_readfirstlane_b32 s2, v4
	v_sub_u32_e32 v4, 0, v3
	v_rcp_iflag_f32_e32 v5, v5
	v_add_u32_e32 v6, s2, v2
	v_mul_f32_e32 v5, 0x4f7ffffe, v5
	v_cvt_u32_f32_e32 v5, v5
	v_mul_lo_u32 v2, v4, v5
	v_mul_hi_u32 v2, v5, v2
	v_add_u32_e32 v2, v5, v2
	v_mul_hi_u32 v2, v6, v2
	v_mul_lo_u32 v4, v2, v3
	v_sub_u32_e32 v4, v6, v4
	v_add_u32_e32 v5, 1, v2
	v_cmp_ge_u32_e32 vcc, v4, v3
	s_nop 1
	v_cndmask_b32_e32 v2, v2, v5, vcc
	v_sub_u32_e32 v5, v4, v3
	v_cndmask_b32_e32 v4, v4, v5, vcc
	v_add_u32_e32 v5, 1, v2
	v_cmp_ge_u32_e32 vcc, v4, v3
	v_add_u32_e32 v4, 1, v6
	s_nop 0
	v_cndmask_b32_e32 v2, v2, v5, vcc
	v_mul_lo_u32 v5, v3, v2
	v_add_u32_e32 v3, v5, v3
	v_cmp_ne_u32_e32 vcc, v4, v3
	s_and_saveexec_b64 s[14:15], vcc
	s_xor_b64 s[14:15], exec, s[14:15]
	s_cbranch_execz .LBB0_513
	s_waitcnt lgkmcnt(0)
	s_add_u32 s44, s8, 0x7500
	s_addc_u32 s45, s9, 0
	v_mov_b32_e32 v0, 0
	global_load_dword v0, v0, s[44:45] sc1
	s_waitcnt vmcnt(0)
	v_cmp_eq_u32_e32 vcc, v0, v2
	s_and_saveexec_b64 s[40:41], vcc
	s_cbranch_execz .LBB0_512
	s_add_u32 s42, s8, 0x4200
	s_addc_u32 s43, s9, 0
	s_mov_b32 s2, 1
	s_mov_b64 s[46:47], 0
	s_branch .LBB0_503

; __device__ __forceinline__ unsigned xb_ld(unsigned* p)              { return __hip_atomic_load(p, __ATOMIC_RELAXED, __HIP_MEMORY_SCOPE_AGENT); }
; __device__ __forceinline__ unsigned xb_add(unsigned* p, unsigned v) { return __hip_atomic_fetch_add(p, v, __ATOMIC_RELAXED, __HIP_MEMORY_SCOPE_AGENT); }
; #define XB_SPIN(cond, bar) do { unsigned _sp = 0; while (cond) { __builtin_amdgcn_s_sleep(1); \
;     if ((++_sp & 255u) == 0u) { if (xb_ld(&(bar)[XB_TMO])) break; if (_sp > XB_SPIN_CAP) { atomicAdd(&(bar)[XB_TMO], 1u); break; } } } } while (0)
; __device__ __forceinline__ void xcd_barrier(const XcdBarrier& b) {
;     ...
;         const unsigned old = xb_add(&bar[XB_XSUB(b.x)], 1u);
;         const unsigned gen = old / nloc;
;         if (old + 1u == (gen + 1u) * nloc) {
;             __builtin_amdgcn_fence(__ATOMIC_RELEASE, "agent");
;             asm volatile("s_waitcnt vmcnt(0)" ::: "memory");
;             const unsigned og = xb_add(&bar[XB_TOP], 1u);
;             const unsigned tg = og / nx;
;             if (og + 1u == (tg + 1u) * nx) xb_add(&bar[XB_TOPGEN], 1u);
;             else XB_SPIN(xb_ld(&bar[XB_TOPGEN]) == tg, bar);
;             __builtin_amdgcn_fence(__ATOMIC_ACQUIRE, "agent");
;             xb_add(&bar[XB_XGEN(b.x)], 1u);
;             asm volatile("s_waitcnt vmcnt(0)" ::: "memory");
;         } else {
;             XB_SPIN(xb_ld(&bar[XB_XGEN(b.x)]) == gen, bar);
;             __builtin_amdgcn_fence(__ATOMIC_ACQUIRE, "agent");
;             asm volatile("s_waitcnt vmcnt(0)" ::: "memory");
;         }
.LBB0_723:
	s_or_b64 exec, exec, s[38:39]
	v_cvt_f32_u32_e32 v5, v3
	s_waitcnt vmcnt(0)
	v_readfirstlane_b32 s2, v4
	v_sub_u32_e32 v4, 0, v3
	v_rcp_iflag_f32_e32 v5, v5
	v_add_u32_e32 v6, s2, v2
	v_mul_f32_e32 v5, 0x4f7ffffe, v5
	v_cvt_u32_f32_e32 v5, v5
	v_mul_lo_u32 v2, v4, v5
	v_mul_hi_u32 v2, v5, v2
	v_add_u32_e32 v2, v5, v2
	v_mul_hi_u32 v2, v6, v2
	v_mul_lo_u32 v4, v2, v3
	v_sub_u32_e32 v4, v6, v4
	v_add_u32_e32 v5, 1, v2
	v_cmp_ge_u32_e32 vcc, v4, v3
	s_nop 1
	v_cndmask_b32_e32 v2, v2, v5, vcc
	v_sub_u32_e32 v5, v4, v3
	v_cndmask_b32_e32 v4, v4, v5, vcc
	v_add_u32_e32 v5, 1, v2
	v_cmp_ge_u32_e32 vcc, v4, v3
	v_add_u32_e32 v4, 1, v6
	s_nop 0
	v_cndmask_b32_e32 v2, v2, v5, vcc
	v_mul_lo_u32 v5, v3, v2
	v_add_u32_e32 v3, v5, v3
	v_cmp_ne_u32_e32 vcc, v4, v3
	s_and_saveexec_b64 s[14:15], vcc
	s_xor_b64 s[14:15], exec, s[14:15]
	s_cbranch_execz .LBB0_737
	s_waitcnt lgkmcnt(0)
	s_add_u32 s42, s8, 0x7500
	s_addc_u32 s43, s9, 0
	v_mov_b32_e32 v0, 0
	global_load_dword v0, v0, s[42:43] sc1
	s_waitcnt vmcnt(0)
	v_cmp_eq_u32_e32 vcc, v0, v2
	s_and_saveexec_b64 s[38:39], vcc
	s_cbranch_execz .LBB0_736
	s_add_u32 s40, s8, 0x4200
	s_addc_u32 s41, s9, 0
	s_mov_b32 s2, 1
	s_mov_b64 s[44:45], 0
	s_branch .LBB0_727

; __device__ __forceinline__ unsigned xb_ld(unsigned* p)              { return __hip_atomic_load(p, __ATOMIC_RELAXED, __HIP_MEMORY_SCOPE_AGENT); }
; __device__ __forceinline__ unsigned xb_add(unsigned* p, unsigned v) { return __hip_atomic_fetch_add(p, v, __ATOMIC_RELAXED, __HIP_MEMORY_SCOPE_AGENT); }
; #define XB_SPIN(cond, bar) do { unsigned _sp = 0; while (cond) { __builtin_amdgcn_s_sleep(1); \
;     if ((++_sp & 255u) == 0u) { if (xb_ld(&(bar)[XB_TMO])) break; if (_sp > XB_SPIN_CAP) { atomicAdd(&(bar)[XB_TMO], 1u); break; } } } } while (0)
; __device__ __forceinline__ void xcd_barrier(const XcdBarrier& b) {
;     ...
;         const unsigned old = xb_add(&bar[XB_XSUB(b.x)], 1u);
;         const unsigned gen = old / nloc;
;         if (old + 1u == (gen + 1u) * nloc) {
;             __builtin_amdgcn_fence(__ATOMIC_RELEASE, "agent");
;             asm volatile("s_waitcnt vmcnt(0)" ::: "memory");
;             const unsigned og = xb_add(&bar[XB_TOP], 1u);
;             const unsigned tg = og / nx;
;             if (og + 1u == (tg + 1u) * nx) xb_add(&bar[XB_TOPGEN], 1u);
;             else XB_SPIN(xb_ld(&bar[XB_TOPGEN]) == tg, bar);
;             __builtin_amdgcn_fence(__ATOMIC_ACQUIRE, "agent");
;             xb_add(&bar[XB_XGEN(b.x)], 1u);
;             asm volatile("s_waitcnt vmcnt(0)" ::: "memory");
;         } else {
;             XB_SPIN(xb_ld(&bar[XB_XGEN(b.x)]) == gen, bar);
;             __builtin_amdgcn_fence(__ATOMIC_ACQUIRE, "agent");
;             asm volatile("s_waitcnt vmcnt(0)" ::: "memory");
;         }
.LBB0_992:
	s_or_b64 exec, exec, s[10:11]
	v_cvt_f32_u32_e32 v4, v2
	s_waitcnt vmcnt(0)
	v_readfirstlane_b32 s8, v3
	v_sub_u32_e32 v3, 0, v2
	v_rcp_iflag_f32_e32 v4, v4
	v_add_u32_e32 v5, s8, v1
	v_mul_f32_e32 v4, 0x4f7ffffe, v4
	v_cvt_u32_f32_e32 v4, v4
	v_mul_lo_u32 v1, v3, v4
	v_mul_hi_u32 v1, v4, v1
	v_add_u32_e32 v1, v4, v1
	v_mul_hi_u32 v1, v5, v1
	v_mul_lo_u32 v3, v1, v2
	v_sub_u32_e32 v3, v5, v3
	v_add_u32_e32 v4, 1, v1
	v_cmp_ge_u32_e32 vcc, v3, v2
	s_nop 1
	v_cndmask_b32_e32 v1, v1, v4, vcc
	v_sub_u32_e32 v4, v3, v2
	v_cndmask_b32_e32 v3, v3, v4, vcc
	v_add_u32_e32 v4, 1, v1
	v_cmp_ge_u32_e32 vcc, v3, v2
	v_add_u32_e32 v3, 1, v5
	s_nop 0
	v_cndmask_b32_e32 v1, v1, v4, vcc
	v_mul_lo_u32 v4, v2, v1
	v_add_u32_e32 v2, v4, v2
	v_cmp_ne_u32_e32 vcc, v3, v2
	s_and_saveexec_b64 s[8:9], vcc
	s_xor_b64 s[8:9], exec, s[8:9]
	s_cbranch_execz .LBB0_1006
	s_waitcnt lgkmcnt(0)
	s_add_u32 s14, s4, 0x7500
	s_addc_u32 s15, s5, 0
	v_mov_b32_e32 v0, 0
	global_load_dword v0, v0, s[14:15] sc1
	s_waitcnt vmcnt(0)
	v_cmp_eq_u32_e32 vcc, v0, v1
	s_and_saveexec_b64 s[10:11], vcc
	s_cbranch_execz .LBB0_1005
	s_add_u32 s12, s4, 0x4200
	s_addc_u32 s13, s5, 0
	s_mov_b32 s26, 1
	s_mov_b64 s[16:17], 0
	v_mov_b32_e32 v0, 0
	s_branch .LBB0_996
